# P4 row statistics of groups 1-5 moved under the residual-load round trips (z already complete there), groups 6-7 in place; packed-f32 + permlane swaps
# speedup vs baseline: 1.0278x; 1.0030x over previous
.LBB0_500:
	s_lshl_b32 s48, s62, 8
	v_add_u32_e32 v134, s48, v196
	v_or_b32_e32 v108, 16, v134
	v_ashrrev_i32_e32 v135, 31, v134
	v_ashrrev_i32_e32 v109, 31, v108
	v_lshlrev_b64 v[184:185], 13, v[134:135]
	v_lshlrev_b64 v[108:109], 13, v[108:109]
	v_lshl_add_u64 v[132:133], v[170:171], 0, v[184:185]
	v_lshl_add_u64 v[108:109], v[170:171], 0, v[108:109]
	v_lshl_add_u64 v[144:145], v[132:133], 0, v[182:183]
	v_lshl_add_u64 v[136:137], v[132:133], 0, v[168:169]
	v_lshl_add_u64 v[186:187], v[108:109], 0, v[182:183]
	v_lshl_add_u64 v[152:153], v[108:109], 0, v[168:169]
	global_load_dwordx4 v[108:111], v[136:137], off offset:128 nt
	s_nop 0
	global_load_dwordx4 v[136:139], v[136:137], off nt
	s_nop 0
	global_load_dwordx4 v[140:143], v[144:145], off offset:128 nt
	s_nop 0
	global_load_dwordx4 v[144:147], v[144:145], off nt
	s_nop 0
	global_load_dwordx4 v[148:151], v[152:153], off offset:128 nt
	s_nop 0
	global_load_dwordx4 v[152:155], v[152:153], off nt
	s_nop 0
	global_load_dwordx4 v[156:159], v[186:187], off offset:128 nt
	s_nop 0
	global_load_dwordx4 v[186:189], v[186:187], off nt
	v_mov_b32_e32 v135, v169
	v_mov_b32_e32 v190, v169
	v_mov_b32_e32 v191, v169
	v_mov_b32_e32 v192, v169
	v_mov_b32_e32 v193, v169
	v_mov_b32_e32 v194, v169
	v_mov_b32_e32 v195, v169
	v_mov_b32_e32 v223, v169
	v_mov_b32_e32 v224, v169
	v_mov_b32_e32 v225, v169
	v_mov_b32_e32 v226, v169
	v_mov_b32_e32 v227, v169
	s_waitcnt vmcnt(0)
	s_nop 0
	v_cndmask_b32_e64 v228, v147, v139, s[0:1]
	v_cndmask_b32_e64 v229, v146, v138, s[0:1]
	v_cndmask_b32_e64 v230, v145, v137, s[0:1]
	v_cndmask_b32_e64 v231, v144, v136, s[0:1]
	v_cndmask_b32_e64 v232, v143, v111, s[0:1]
	v_cndmask_b32_e64 v233, v142, v110, s[0:1]
	v_cndmask_b32_e64 v234, v141, v109, s[0:1]
	v_cndmask_b32_e64 v235, v140, v108, s[0:1]
	v_mov_b32_dpp v135, v231 row_ror:8 row_mask:0xf bank_mask:0xf
	v_mov_b32_dpp v190, v230 row_ror:8 row_mask:0xf bank_mask:0xf
	v_mov_b32_dpp v191, v229 row_ror:8 row_mask:0xf bank_mask:0xf
	v_mov_b32_dpp v192, v228 row_ror:8 row_mask:0xf bank_mask:0xf
	v_mov_b32_dpp v193, v235 row_ror:8 row_mask:0xf bank_mask:0xf
	v_mov_b32_dpp v194, v234 row_ror:8 row_mask:0xf bank_mask:0xf
	v_mov_b32_dpp v195, v233 row_ror:8 row_mask:0xf bank_mask:0xf
	v_mov_b32_dpp v223, v232 row_ror:8 row_mask:0xf bank_mask:0xf
	v_cndmask_b32_e64 v228, v189, v155, s[0:1]
	v_cndmask_b32_e64 v229, v188, v154, s[0:1]
	v_cndmask_b32_e64 v230, v187, v153, s[0:1]
	v_cndmask_b32_e64 v231, v186, v152, s[0:1]
	v_cndmask_b32_e64 v136, v136, v135, s[0:1]
	v_cndmask_b32_e64 v145, v190, v145, s[0:1]
	v_cndmask_b32_e64 v137, v137, v190, s[0:1]
	v_cndmask_b32_e64 v146, v191, v146, s[0:1]
	v_cndmask_b32_e64 v138, v138, v191, s[0:1]
	v_cndmask_b32_e64 v147, v192, v147, s[0:1]
	v_cndmask_b32_e64 v139, v139, v192, s[0:1]
	v_cndmask_b32_e64 v140, v193, v140, s[0:1]
	v_cndmask_b32_e64 v190, v108, v193, s[0:1]
	v_cndmask_b32_e64 v191, v109, v194, s[0:1]
	v_cndmask_b32_e64 v192, v110, v195, s[0:1]
	v_cndmask_b32_e64 v193, v111, v223, s[0:1]
	v_mov_b32_dpp v224, v231 row_ror:8 row_mask:0xf bank_mask:0xf
	v_mov_b32_dpp v225, v230 row_ror:8 row_mask:0xf bank_mask:0xf
	v_mov_b32_dpp v226, v229 row_ror:8 row_mask:0xf bank_mask:0xf
	v_mov_b32_dpp v227, v228 row_ror:8 row_mask:0xf bank_mask:0xf
	v_pk_fma_f32 v[110:111], v[138:139], s[28:29], v[98:99] op_sel_hi:[1,0,1]
	v_pk_fma_f32 v[108:109], v[136:137], s[28:29], v[96:97] op_sel_hi:[1,0,1]
	v_pk_fma_f32 v[98:99], v[192:193], s[28:29], v[74:75] op_sel_hi:[1,0,1]
	v_pk_fma_f32 v[96:97], v[190:191], s[28:29], v[72:73] op_sel_hi:[1,0,1]
	v_cndmask_b32_e64 v72, v224, v186, s[0:1]
	v_cndmask_b32_e64 v73, v225, v187, s[0:1]
	v_cndmask_b32_e64 v74, v226, v188, s[0:1]
	v_cndmask_b32_e64 v75, v227, v189, s[0:1]
	v_pk_fma_f32 v[74:75], v[74:75], s[28:29], v[130:131] op_sel_hi:[1,0,1]
	v_pk_fma_f32 v[72:73], v[72:73], s[28:29], v[128:129] op_sel_hi:[1,0,1]
	v_cndmask_b32_e64 v129, v157, v149, s[0:1]
	v_cndmask_b32_e64 v128, v156, v148, s[0:1]
	v_mov_b32_e32 v130, v169
	v_mov_b32_e32 v131, v169
	v_cndmask_b32_e64 v136, v152, v224, s[0:1]
	v_mov_b32_dpp v130, v128 row_ror:8 row_mask:0xf bank_mask:0xf
	v_mov_b32_dpp v131, v129 row_ror:8 row_mask:0xf bank_mask:0xf
	v_cndmask_b32_e64 v128, v130, v156, s[0:1]
	v_cndmask_b32_e64 v129, v131, v157, s[0:1]
	v_cndmask_b32_e64 v137, v153, v225, s[0:1]
	v_cndmask_b32_e64 v138, v154, v226, s[0:1]
	v_cndmask_b32_e64 v139, v155, v227, s[0:1]
	v_pk_fma_f32 v[64:65], v[128:129], s[28:29], v[64:65] op_sel_hi:[1,0,1]
	v_or_b32_e32 v128, 32, v134
	v_cndmask_b32_e64 v144, v135, v144, s[0:1]
	v_pk_fma_f32 v[78:79], v[138:139], s[28:29], v[78:79] op_sel_hi:[1,0,1]
	v_pk_fma_f32 v[76:77], v[136:137], s[28:29], v[76:77] op_sel_hi:[1,0,1]
	v_cndmask_b32_e64 v135, v159, v151, s[0:1]
	v_cndmask_b32_e64 v136, v158, v150, s[0:1]
	v_mov_b32_e32 v137, v169
	v_mov_b32_e32 v139, v169
	v_ashrrev_i32_e32 v129, 31, v128
	v_mov_b32_dpp v137, v136 row_ror:8 row_mask:0xf bank_mask:0xf
	v_mov_b32_dpp v139, v135 row_ror:8 row_mask:0xf bank_mask:0xf
	v_lshlrev_b64 v[128:129], 13, v[128:129]
	v_cndmask_b32_e64 v142, v195, v142, s[0:1]
	v_cndmask_b32_e64 v143, v223, v143, s[0:1]
	v_cndmask_b32_e64 v136, v137, v158, s[0:1]
	v_cndmask_b32_e64 v138, v150, v137, s[0:1]
	v_cndmask_b32_e64 v137, v139, v159, s[0:1]
	v_lshl_add_u64 v[128:129], v[170:171], 0, v[128:129]
	v_pk_fma_f32 v[94:95], v[142:143], s[28:29], v[94:95] op_sel_hi:[1,0,1]
	v_pk_fma_f32 v[66:67], v[136:137], s[28:29], v[66:67] op_sel_hi:[1,0,1]
	v_lshl_add_u64 v[142:143], v[128:129], 0, v[182:183]
	v_lshl_add_u64 v[136:137], v[128:129], 0, v[168:169]
	v_or_b32_e32 v128, 48, v134
	v_ashrrev_i32_e32 v129, 31, v128
	v_cndmask_b32_e64 v141, v194, v141, s[0:1]
	v_cndmask_b32_e64 v130, v148, v130, s[0:1]
	v_cndmask_b32_e64 v131, v149, v131, s[0:1]
	v_cndmask_b32_e64 v139, v151, v139, s[0:1]
	v_lshlrev_b64 v[128:129], 13, v[128:129]
	v_pk_fma_f32 v[102:103], v[146:147], s[28:29], v[102:103] op_sel_hi:[1,0,1]
	v_pk_fma_f32 v[100:101], v[144:145], s[28:29], v[100:101] op_sel_hi:[1,0,1]
	v_pk_fma_f32 v[92:93], v[140:141], s[28:29], v[92:93] op_sel_hi:[1,0,1]
	v_pk_fma_f32 v[70:71], v[138:139], s[28:29], v[70:71] op_sel_hi:[1,0,1]
	v_pk_fma_f32 v[68:69], v[130:131], s[28:29], v[68:69] op_sel_hi:[1,0,1]
	v_lshl_add_u64 v[128:129], v[170:171], 0, v[128:129]
	v_lshl_add_u64 v[150:151], v[128:129], 0, v[168:169]
	v_lshl_add_u64 v[158:159], v[128:129], 0, v[182:183]
	global_load_dwordx4 v[128:131], v[136:137], off offset:128 nt
	s_nop 0
	global_load_dwordx4 v[134:137], v[136:137], off nt
	s_nop 0
	global_load_dwordx4 v[138:141], v[142:143], off offset:128 nt
	s_nop 0
	global_load_dwordx4 v[142:145], v[142:143], off nt
	s_nop 0
	global_load_dwordx4 v[146:149], v[150:151], off offset:128 nt
	s_nop 0
	global_load_dwordx4 v[150:153], v[150:151], off nt
	s_nop 0
	global_load_dwordx4 v[154:157], v[158:159], off offset:128 nt
	global_load_dwordx4 v[186:189], v[158:159], off nt
	v_pk_add_f32 v[236:237], v[64:65], v[66:67]
	v_pk_add_f32 v[238:239], v[68:69], v[70:71]
	v_pk_add_f32 v[240:241], v[72:73], v[74:75]
	v_pk_add_f32 v[242:243], v[76:77], v[78:79]
	v_pk_add_f32 v[236:237], v[236:237], v[238:239]
	v_pk_add_f32 v[240:241], v[240:241], v[242:243]
	s_nop 0
	v_pk_add_f32 v[236:237], v[236:237], v[240:241]
	s_nop 0
	v_add_f32_e32 v236, v236, v237
	v_mov_b32_e32 v237, v236
	s_nop 1
	v_permlane16_swap_b32_e32 v236, v237
	v_add_f32_e32 v236, v236, v237
	v_mov_b32_e32 v237, v236
	s_nop 1
	v_permlane32_swap_b32_e32 v236, v237
	v_add_f32_e32 v236, v236, v237
	v_mul_f32_e32 v238, 0xbc800000, v236
	s_nop 0
	v_pk_add_f32 v[240:241], v[64:65], v[238:239] op_sel_hi:[1,0]
	v_pk_add_f32 v[244:245], v[66:67], v[238:239] op_sel_hi:[1,0]
	v_pk_mul_f32 v[242:243], v[240:241], v[240:241]
	v_pk_mul_f32 v[246:247], v[244:245], v[244:245]
	v_pk_add_f32 v[240:241], v[68:69], v[238:239] op_sel_hi:[1,0]
	v_pk_add_f32 v[244:245], v[70:71], v[238:239] op_sel_hi:[1,0]
	v_pk_fma_f32 v[242:243], v[240:241], v[240:241], v[242:243]
	v_pk_fma_f32 v[246:247], v[244:245], v[244:245], v[246:247]
	v_pk_add_f32 v[240:241], v[72:73], v[238:239] op_sel_hi:[1,0]
	v_pk_add_f32 v[244:245], v[74:75], v[238:239] op_sel_hi:[1,0]
	v_pk_fma_f32 v[242:243], v[240:241], v[240:241], v[242:243]
	v_pk_fma_f32 v[246:247], v[244:245], v[244:245], v[246:247]
	v_pk_add_f32 v[240:241], v[76:77], v[238:239] op_sel_hi:[1,0]
	v_pk_add_f32 v[244:245], v[78:79], v[238:239] op_sel_hi:[1,0]
	v_pk_fma_f32 v[242:243], v[240:241], v[240:241], v[242:243]
	v_pk_fma_f32 v[246:247], v[244:245], v[244:245], v[246:247]
	s_nop 0
	v_pk_add_f32 v[242:243], v[242:243], v[246:247]
	s_nop 0
	v_add_f32_e32 v237, v242, v243
	v_mov_b32_e32 v238, v237
	s_nop 1
	v_permlane16_swap_b32_e32 v237, v238
	v_add_f32_e32 v237, v237, v238
	v_mov_b32_e32 v238, v237
	s_nop 1
	v_permlane32_swap_b32_e32 v237, v238
	v_add_f32_e32 v237, v237, v238
	s_and_saveexec_b64 s[8:9], s[2:3]
	s_cbranch_execz .Lst_e1
	v_mul_f32_e32 v236, 0x3c800000, v236
	ds_write_b64 v222, v[236:237] offset:512
.Lst_e1:
	s_or_b64 exec, exec, s[8:9]
	v_mov_b32_e32 v158, v169
	v_mov_b32_e32 v159, v169
	v_mov_b32_e32 v190, v169
	v_mov_b32_e32 v191, v169
	s_waitcnt vmcnt(4)
	s_nop 0
	v_cndmask_b32_e64 v194, v145, v137, s[0:1]
	v_cndmask_b32_e64 v195, v144, v136, s[0:1]
	v_cndmask_b32_e64 v223, v143, v135, s[0:1]
	v_cndmask_b32_e64 v224, v142, v134, s[0:1]
	v_mov_b32_dpp v190, v195 row_ror:8 row_mask:0xf bank_mask:0xf
	v_mov_b32_dpp v159, v223 row_ror:8 row_mask:0xf bank_mask:0xf
	v_mov_b32_dpp v158, v224 row_ror:8 row_mask:0xf bank_mask:0xf
	v_mov_b32_dpp v191, v194 row_ror:8 row_mask:0xf bank_mask:0xf
	v_cndmask_b32_e64 v134, v134, v158, s[0:1]
	v_cndmask_b32_e64 v135, v135, v159, s[0:1]
	v_cndmask_b32_e64 v136, v136, v190, s[0:1]
	v_cndmask_b32_e64 v137, v137, v191, s[0:1]
	v_mov_b32_e32 v192, v169
	v_mov_b32_e32 v193, v169
	v_cndmask_b32_e64 v225, v141, v131, s[0:1]
	v_cndmask_b32_e64 v226, v140, v130, s[0:1]
	v_cndmask_b32_e64 v227, v139, v129, s[0:1]
	v_cndmask_b32_e64 v228, v138, v128, s[0:1]
	v_pk_fma_f32 v[122:123], v[136:137], s[28:29], v[122:123] op_sel_hi:[1,0,1]
	v_pk_fma_f32 v[120:121], v[134:135], s[28:29], v[120:121] op_sel_hi:[1,0,1]
	v_mov_b32_e32 v135, v169
	v_mov_b32_e32 v136, v169
	v_mov_b32_dpp v192, v228 row_ror:8 row_mask:0xf bank_mask:0xf
	v_mov_b32_dpp v193, v227 row_ror:8 row_mask:0xf bank_mask:0xf
	v_mov_b32_dpp v135, v226 row_ror:8 row_mask:0xf bank_mask:0xf
	v_mov_b32_dpp v136, v225 row_ror:8 row_mask:0xf bank_mask:0xf
	v_cndmask_b32_e64 v128, v128, v192, s[0:1]
	v_cndmask_b32_e64 v129, v129, v193, s[0:1]
	v_cndmask_b32_e64 v130, v130, v135, s[0:1]
	v_cndmask_b32_e64 v131, v131, v136, s[0:1]
	s_waitcnt vmcnt(0)
	v_cndmask_b32_e64 v134, v135, v140, s[0:1]
	v_cndmask_b32_e64 v135, v136, v141, s[0:1]
	v_pk_fma_f32 v[106:107], v[130:131], s[28:29], v[106:107] op_sel_hi:[1,0,1]
	v_pk_fma_f32 v[104:105], v[128:129], s[28:29], v[104:105] op_sel_hi:[1,0,1]
	v_cndmask_b32_e64 v129, v187, v151, s[0:1]
	v_cndmask_b32_e64 v128, v186, v150, s[0:1]
	v_mov_b32_e32 v130, v169
	v_mov_b32_e32 v131, v169
	v_pk_fma_f32 v[86:87], v[134:135], s[28:29], v[86:87] op_sel_hi:[1,0,1]
	v_cndmask_b32_e64 v135, v189, v153, s[0:1]
	v_cndmask_b32_e64 v134, v188, v152, s[0:1]
	v_mov_b32_dpp v130, v128 row_ror:8 row_mask:0xf bank_mask:0xf
	v_mov_b32_dpp v131, v129 row_ror:8 row_mask:0xf bank_mask:0xf
	v_mov_b32_e32 v136, v169
	v_mov_b32_e32 v137, v169
	v_cndmask_b32_e64 v128, v130, v186, s[0:1]
	v_cndmask_b32_e64 v130, v150, v130, s[0:1]
	v_cndmask_b32_e64 v129, v131, v187, s[0:1]
	v_cndmask_b32_e64 v131, v151, v131, s[0:1]
	v_mov_b32_dpp v136, v134 row_ror:8 row_mask:0xf bank_mask:0xf
	v_mov_b32_dpp v137, v135 row_ror:8 row_mask:0xf bank_mask:0xf
	v_cndmask_b32_e64 v134, v136, v188, s[0:1]
	v_cndmask_b32_e64 v136, v152, v136, s[0:1]
	v_cndmask_b32_e64 v135, v137, v189, s[0:1]
	v_cndmask_b32_e64 v137, v153, v137, s[0:1]
	v_pk_fma_f32 v[112:113], v[128:129], s[28:29], v[112:113] op_sel_hi:[1,0,1]
	v_pk_fma_f32 v[116:117], v[130:131], s[28:29], v[116:117] op_sel_hi:[1,0,1]
	v_cndmask_b32_e64 v129, v155, v147, s[0:1]
	v_cndmask_b32_e64 v128, v154, v146, s[0:1]
	v_mov_b32_e32 v130, v169
	v_mov_b32_e32 v131, v169
	v_pk_fma_f32 v[114:115], v[134:135], s[28:29], v[114:115] op_sel_hi:[1,0,1]
	v_pk_fma_f32 v[118:119], v[136:137], s[28:29], v[118:119] op_sel_hi:[1,0,1]
	v_cndmask_b32_e64 v135, v157, v149, s[0:1]
	v_cndmask_b32_e64 v134, v156, v148, s[0:1]
	v_mov_b32_dpp v130, v128 row_ror:8 row_mask:0xf bank_mask:0xf
	v_mov_b32_dpp v131, v129 row_ror:8 row_mask:0xf bank_mask:0xf
	v_mov_b32_e32 v136, v169
	v_mov_b32_e32 v137, v169
	v_cndmask_b32_e64 v128, v130, v154, s[0:1]
	v_cndmask_b32_e64 v129, v131, v155, s[0:1]
	v_mov_b32_dpp v136, v134 row_ror:8 row_mask:0xf bank_mask:0xf
	v_mov_b32_dpp v137, v135 row_ror:8 row_mask:0xf bank_mask:0xf
	v_cndmask_b32_e64 v142, v158, v142, s[0:1]
	v_cndmask_b32_e64 v143, v159, v143, s[0:1]
	v_cndmask_b32_e64 v144, v190, v144, s[0:1]
	v_cndmask_b32_e64 v145, v191, v145, s[0:1]
	v_cndmask_b32_e64 v138, v192, v138, s[0:1]
	v_cndmask_b32_e64 v139, v193, v139, s[0:1]
	v_cndmask_b32_e64 v130, v146, v130, s[0:1]
	v_cndmask_b32_e64 v131, v147, v131, s[0:1]
	v_cndmask_b32_e64 v134, v136, v156, s[0:1]
	v_cndmask_b32_e64 v136, v148, v136, s[0:1]
	v_cndmask_b32_e64 v135, v137, v157, s[0:1]
	v_cndmask_b32_e64 v137, v149, v137, s[0:1]
	v_pk_fma_f32 v[80:81], v[128:129], s[28:29], v[80:81] op_sel_hi:[1,0,1]
	v_lshl_add_u64 v[128:129], v[132:133], 0, s[30:31]
	v_pk_fma_f32 v[126:127], v[144:145], s[28:29], v[126:127] op_sel_hi:[1,0,1]
	v_pk_fma_f32 v[124:125], v[142:143], s[28:29], v[124:125] op_sel_hi:[1,0,1]
	v_pk_fma_f32 v[84:85], v[138:139], s[28:29], v[84:85] op_sel_hi:[1,0,1]
	v_pk_fma_f32 v[82:83], v[134:135], s[28:29], v[82:83] op_sel_hi:[1,0,1]
	v_pk_fma_f32 v[90:91], v[136:137], s[28:29], v[90:91] op_sel_hi:[1,0,1]
	v_pk_fma_f32 v[88:89], v[130:131], s[28:29], v[88:89] op_sel_hi:[1,0,1]
	v_lshl_add_u64 v[142:143], v[128:129], 0, v[182:183]
	v_lshl_add_u64 v[134:135], v[128:129], 0, v[168:169]
	v_lshl_add_u64 v[128:129], v[132:133], 0, s[34:35]
	v_lshl_add_u64 v[150:151], v[128:129], 0, v[168:169]
	v_lshl_add_u64 v[158:159], v[128:129], 0, v[182:183]
	global_load_dwordx4 v[128:131], v[134:135], off offset:128 nt
	s_nop 0
	global_load_dwordx4 v[134:137], v[134:135], off nt
	s_nop 0
	global_load_dwordx4 v[138:141], v[142:143], off offset:128 nt
	s_nop 0
	global_load_dwordx4 v[142:145], v[142:143], off nt
	s_nop 0
	global_load_dwordx4 v[146:149], v[150:151], off offset:128 nt
	s_nop 0
	global_load_dwordx4 v[150:153], v[150:151], off nt
	s_nop 0
	global_load_dwordx4 v[154:157], v[158:159], off offset:128 nt
	global_load_dwordx4 v[186:189], v[158:159], off nt
	v_pk_add_f32 v[236:237], v[84:85], v[86:87]
	v_pk_add_f32 v[238:239], v[104:105], v[106:107]
	v_pk_add_f32 v[240:241], v[120:121], v[122:123]
	v_pk_add_f32 v[242:243], v[124:125], v[126:127]
	v_pk_add_f32 v[236:237], v[236:237], v[238:239]
	v_pk_add_f32 v[240:241], v[240:241], v[242:243]
	s_nop 0
	v_pk_add_f32 v[236:237], v[236:237], v[240:241]
	s_nop 0
	v_add_f32_e32 v236, v236, v237
	v_mov_b32_e32 v237, v236
	s_nop 1
	v_permlane16_swap_b32_e32 v236, v237
	v_add_f32_e32 v236, v236, v237
	v_mov_b32_e32 v237, v236
	s_nop 1
	v_permlane32_swap_b32_e32 v236, v237
	v_add_f32_e32 v236, v236, v237
	v_mul_f32_e32 v238, 0xbc800000, v236
	s_nop 0
	v_pk_add_f32 v[240:241], v[84:85], v[238:239] op_sel_hi:[1,0]
	v_pk_add_f32 v[244:245], v[86:87], v[238:239] op_sel_hi:[1,0]
	v_pk_mul_f32 v[242:243], v[240:241], v[240:241]
	v_pk_mul_f32 v[246:247], v[244:245], v[244:245]
	v_pk_add_f32 v[240:241], v[104:105], v[238:239] op_sel_hi:[1,0]
	v_pk_add_f32 v[244:245], v[106:107], v[238:239] op_sel_hi:[1,0]
	v_pk_fma_f32 v[242:243], v[240:241], v[240:241], v[242:243]
	v_pk_fma_f32 v[246:247], v[244:245], v[244:245], v[246:247]
	v_pk_add_f32 v[240:241], v[120:121], v[238:239] op_sel_hi:[1,0]
	v_pk_add_f32 v[244:245], v[122:123], v[238:239] op_sel_hi:[1,0]
	v_pk_fma_f32 v[242:243], v[240:241], v[240:241], v[242:243]
	v_pk_fma_f32 v[246:247], v[244:245], v[244:245], v[246:247]
	v_pk_add_f32 v[240:241], v[124:125], v[238:239] op_sel_hi:[1,0]
	v_pk_add_f32 v[244:245], v[126:127], v[238:239] op_sel_hi:[1,0]
	v_pk_fma_f32 v[242:243], v[240:241], v[240:241], v[242:243]
	v_pk_fma_f32 v[246:247], v[244:245], v[244:245], v[246:247]
	s_nop 0
	v_pk_add_f32 v[242:243], v[242:243], v[246:247]
	s_nop 0
	v_add_f32_e32 v237, v242, v243
	v_mov_b32_e32 v238, v237
	s_nop 1
	v_permlane16_swap_b32_e32 v237, v238
	v_add_f32_e32 v237, v237, v238
	v_mov_b32_e32 v238, v237
	s_nop 1
	v_permlane32_swap_b32_e32 v237, v238
	v_add_f32_e32 v237, v237, v238
	s_and_saveexec_b64 s[8:9], s[2:3]
	s_cbranch_execz .Lst_e2
	v_mul_f32_e32 v236, 0x3c800000, v236
	ds_write_b64 v222, v[236:237] offset:1024
.Lst_e2:
	s_or_b64 exec, exec, s[8:9]
	v_pk_add_f32 v[236:237], v[80:81], v[82:83]
	v_pk_add_f32 v[238:239], v[88:89], v[90:91]
	v_pk_add_f32 v[240:241], v[112:113], v[114:115]
	v_pk_add_f32 v[242:243], v[116:117], v[118:119]
	v_pk_add_f32 v[236:237], v[236:237], v[238:239]
	v_pk_add_f32 v[240:241], v[240:241], v[242:243]
	s_nop 0
	v_pk_add_f32 v[236:237], v[236:237], v[240:241]
	s_nop 0
	v_add_f32_e32 v236, v236, v237
	v_mov_b32_e32 v237, v236
	s_nop 1
	v_permlane16_swap_b32_e32 v236, v237
	v_add_f32_e32 v236, v236, v237
	v_mov_b32_e32 v237, v236
	s_nop 1
	v_permlane32_swap_b32_e32 v236, v237
	v_add_f32_e32 v236, v236, v237
	v_mul_f32_e32 v238, 0xbc800000, v236
	s_nop 0
	v_pk_add_f32 v[240:241], v[80:81], v[238:239] op_sel_hi:[1,0]
	v_pk_add_f32 v[244:245], v[82:83], v[238:239] op_sel_hi:[1,0]
	v_pk_mul_f32 v[242:243], v[240:241], v[240:241]
	v_pk_mul_f32 v[246:247], v[244:245], v[244:245]
	v_pk_add_f32 v[240:241], v[88:89], v[238:239] op_sel_hi:[1,0]
	v_pk_add_f32 v[244:245], v[90:91], v[238:239] op_sel_hi:[1,0]
	v_pk_fma_f32 v[242:243], v[240:241], v[240:241], v[242:243]
	v_pk_fma_f32 v[246:247], v[244:245], v[244:245], v[246:247]
	v_pk_add_f32 v[240:241], v[112:113], v[238:239] op_sel_hi:[1,0]
	v_pk_add_f32 v[244:245], v[114:115], v[238:239] op_sel_hi:[1,0]
	v_pk_fma_f32 v[242:243], v[240:241], v[240:241], v[242:243]
	v_pk_fma_f32 v[246:247], v[244:245], v[244:245], v[246:247]
	v_pk_add_f32 v[240:241], v[116:117], v[238:239] op_sel_hi:[1,0]
	v_pk_add_f32 v[244:245], v[118:119], v[238:239] op_sel_hi:[1,0]
	v_pk_fma_f32 v[242:243], v[240:241], v[240:241], v[242:243]
	v_pk_fma_f32 v[246:247], v[244:245], v[244:245], v[246:247]
	s_nop 0
	v_pk_add_f32 v[242:243], v[242:243], v[246:247]
	s_nop 0
	v_add_f32_e32 v237, v242, v243
	v_mov_b32_e32 v238, v237
	s_nop 1
	v_permlane16_swap_b32_e32 v237, v238
	v_add_f32_e32 v237, v237, v238
	v_mov_b32_e32 v238, v237
	s_nop 1
	v_permlane32_swap_b32_e32 v237, v238
	v_add_f32_e32 v237, v237, v238
	s_and_saveexec_b64 s[8:9], s[2:3]
	s_cbranch_execz .Lst_e3
	v_mul_f32_e32 v236, 0x3c800000, v236
	ds_write_b64 v222, v[236:237] offset:1536
.Lst_e3:
	s_or_b64 exec, exec, s[8:9]
	s_waitcnt vmcnt(4)
	s_nop 0
	v_cndmask_b32_e64 v191, v142, v134, s[0:1]
	v_mov_b32_e32 v192, v169
	v_cndmask_b32_e64 v190, v143, v135, s[0:1]
	v_cndmask_b32_e64 v159, v144, v136, s[0:1]
	v_mov_b32_dpp v192, v191 row_ror:8 row_mask:0xf bank_mask:0xf
	v_mov_b32_e32 v191, v169
	v_cndmask_b32_e64 v142, v192, v142, s[0:1]
	v_cndmask_b32_e64 v134, v134, v192, s[0:1]
	v_mov_b32_dpp v191, v190 row_ror:8 row_mask:0xf bank_mask:0xf
	v_cndmask_b32_e64 v143, v191, v143, s[0:1]
	v_cndmask_b32_e64 v135, v135, v191, s[0:1]
	v_mov_b32_e32 v190, v169
	v_pk_fma_f32 v[12:13], v[142:143], s[28:29], v[12:13] op_sel_hi:[1,0,1]
	v_pk_fma_f32 v[20:21], v[134:135], s[28:29], v[20:21] op_sel_hi:[1,0,1]
	v_cndmask_b32_e64 v134, v138, v128, s[0:1]
	v_mov_b32_e32 v142, v169
	v_cndmask_b32_e64 v158, v145, v137, s[0:1]
	v_mov_b32_dpp v190, v159 row_ror:8 row_mask:0xf bank_mask:0xf
	v_mov_b32_e32 v159, v169
	v_mov_b32_dpp v142, v134 row_ror:8 row_mask:0xf bank_mask:0xf
	v_cndmask_b32_e64 v135, v139, v129, s[0:1]
	v_mov_b32_dpp v159, v158 row_ror:8 row_mask:0xf bank_mask:0xf
	v_cndmask_b32_e64 v134, v142, v138, s[0:1]
	v_mov_b32_e32 v138, v169
	v_cndmask_b32_e64 v136, v136, v190, s[0:1]
	v_cndmask_b32_e64 v137, v137, v159, s[0:1]
	v_mov_b32_dpp v138, v135 row_ror:8 row_mask:0xf bank_mask:0xf
	v_pk_fma_f32 v[22:23], v[136:137], s[28:29], v[22:23] op_sel_hi:[1,0,1]
	v_cndmask_b32_e64 v136, v140, v130, s[0:1]
	v_cndmask_b32_e64 v135, v138, v139, s[0:1]
	v_cndmask_b32_e64 v129, v129, v138, s[0:1]
	v_mov_b32_e32 v138, v169
	v_cndmask_b32_e64 v137, v141, v131, s[0:1]
	v_cndmask_b32_e64 v128, v128, v142, s[0:1]
	v_mov_b32_dpp v138, v136 row_ror:8 row_mask:0xf bank_mask:0xf
	v_cndmask_b32_e64 v136, v138, v140, s[0:1]
	v_cndmask_b32_e64 v130, v130, v138, s[0:1]
	v_mov_b32_e32 v138, v169
	s_waitcnt vmcnt(0)
	v_pk_fma_f32 v[0:1], v[134:135], s[28:29], v[0:1] op_sel_hi:[1,0,1]
	v_pk_fma_f32 v[4:5], v[128:129], s[28:29], v[4:5] op_sel_hi:[1,0,1]
	v_mov_b32_dpp v138, v137 row_ror:8 row_mask:0xf bank_mask:0xf
	v_cndmask_b32_e64 v137, v138, v141, s[0:1]
	v_cndmask_b32_e64 v131, v131, v138, s[0:1]
	v_pk_fma_f32 v[2:3], v[136:137], s[28:29], v[2:3] op_sel_hi:[1,0,1]
	v_pk_fma_f32 v[6:7], v[130:131], s[28:29], v[6:7] op_sel_hi:[1,0,1]
	v_cndmask_b32_e64 v135, v189, v153, s[0:1]
	v_cndmask_b32_e64 v134, v188, v152, s[0:1]
	v_cndmask_b32_e64 v129, v187, v151, s[0:1]
	v_cndmask_b32_e64 v128, v186, v150, s[0:1]
	v_mov_b32_e32 v130, v169
	v_mov_b32_e32 v131, v169
	v_mov_b32_e32 v136, v169
	v_mov_b32_e32 v137, v169
	v_mov_b32_dpp v130, v128 row_ror:8 row_mask:0xf bank_mask:0xf
	v_mov_b32_dpp v131, v129 row_ror:8 row_mask:0xf bank_mask:0xf
	v_mov_b32_dpp v136, v134 row_ror:8 row_mask:0xf bank_mask:0xf
	v_mov_b32_dpp v137, v135 row_ror:8 row_mask:0xf bank_mask:0xf
	v_cndmask_b32_e64 v128, v130, v186, s[0:1]
	v_cndmask_b32_e64 v130, v150, v130, s[0:1]
	v_cndmask_b32_e64 v129, v131, v187, s[0:1]
	v_cndmask_b32_e64 v131, v151, v131, s[0:1]
	v_cndmask_b32_e64 v134, v136, v188, s[0:1]
	v_cndmask_b32_e64 v136, v152, v136, s[0:1]
	v_cndmask_b32_e64 v135, v137, v189, s[0:1]
	v_cndmask_b32_e64 v137, v153, v137, s[0:1]
	v_pk_fma_f32 v[26:27], v[134:135], s[28:29], v[26:27] op_sel_hi:[1,0,1]
	v_pk_fma_f32 v[24:25], v[128:129], s[28:29], v[24:25] op_sel_hi:[1,0,1]
	v_pk_fma_f32 v[30:31], v[136:137], s[28:29], v[30:31] op_sel_hi:[1,0,1]
	v_pk_fma_f32 v[28:29], v[130:131], s[28:29], v[28:29] op_sel_hi:[1,0,1]
	v_cndmask_b32_e64 v135, v157, v149, s[0:1]
	v_cndmask_b32_e64 v134, v156, v148, s[0:1]
	v_cndmask_b32_e64 v129, v155, v147, s[0:1]
	v_cndmask_b32_e64 v128, v154, v146, s[0:1]
	v_mov_b32_e32 v130, v169
	v_mov_b32_e32 v131, v169
	v_mov_b32_e32 v136, v169
	v_mov_b32_e32 v137, v169
	v_mov_b32_dpp v130, v128 row_ror:8 row_mask:0xf bank_mask:0xf
	v_mov_b32_dpp v131, v129 row_ror:8 row_mask:0xf bank_mask:0xf
	v_mov_b32_dpp v136, v134 row_ror:8 row_mask:0xf bank_mask:0xf
	v_mov_b32_dpp v137, v135 row_ror:8 row_mask:0xf bank_mask:0xf
	v_cndmask_b32_e64 v144, v190, v144, s[0:1]
	v_cndmask_b32_e64 v145, v159, v145, s[0:1]
	v_cndmask_b32_e64 v128, v130, v154, s[0:1]
	v_cndmask_b32_e64 v130, v146, v130, s[0:1]
	v_cndmask_b32_e64 v129, v131, v155, s[0:1]
	v_cndmask_b32_e64 v131, v147, v131, s[0:1]
	v_cndmask_b32_e64 v134, v136, v156, s[0:1]
	v_cndmask_b32_e64 v136, v148, v136, s[0:1]
	v_cndmask_b32_e64 v135, v137, v157, s[0:1]
	v_cndmask_b32_e64 v137, v149, v137, s[0:1]
	v_pk_fma_f32 v[14:15], v[144:145], s[28:29], v[14:15] op_sel_hi:[1,0,1]
	v_pk_fma_f32 v[10:11], v[134:135], s[28:29], v[10:11] op_sel_hi:[1,0,1]
	v_pk_fma_f32 v[8:9], v[128:129], s[28:29], v[8:9] op_sel_hi:[1,0,1]
	v_pk_fma_f32 v[18:19], v[136:137], s[28:29], v[18:19] op_sel_hi:[1,0,1]
	v_pk_fma_f32 v[16:17], v[130:131], s[28:29], v[16:17] op_sel_hi:[1,0,1]
	v_lshl_add_u64 v[128:129], v[132:133], 0, s[40:41]
	v_lshl_add_u64 v[132:133], v[132:133], 0, s[42:43]
	v_lshl_add_u64 v[130:131], v[128:129], 0, v[182:183]
	v_lshl_add_u64 v[128:129], v[128:129], 0, v[168:169]
	v_lshl_add_u64 v[156:157], v[132:133], 0, v[182:183]
	v_lshl_add_u64 v[148:149], v[132:133], 0, v[168:169]
	global_load_dwordx4 v[132:135], v[128:129], off offset:128 nt
	global_load_dwordx4 v[136:139], v[128:129], off nt
	global_load_dwordx4 v[140:143], v[130:131], off offset:128 nt
	global_load_dwordx4 v[144:147], v[130:131], off nt
	s_nop 0
	global_load_dwordx4 v[128:131], v[148:149], off offset:128 nt
	s_nop 0
	global_load_dwordx4 v[148:151], v[148:149], off nt
	s_nop 0
	global_load_dwordx4 v[152:155], v[156:157], off offset:128 nt
	s_nop 0
	global_load_dwordx4 v[156:159], v[156:157], off nt
	v_pk_add_f32 v[236:237], v[0:1], v[2:3]
	v_pk_add_f32 v[238:239], v[4:5], v[6:7]
	v_pk_add_f32 v[240:241], v[12:13], v[14:15]
	v_pk_add_f32 v[242:243], v[20:21], v[22:23]
	v_pk_add_f32 v[236:237], v[236:237], v[238:239]
	v_pk_add_f32 v[240:241], v[240:241], v[242:243]
	s_nop 0
	v_pk_add_f32 v[236:237], v[236:237], v[240:241]
	s_nop 0
	v_add_f32_e32 v236, v236, v237
	v_mov_b32_e32 v237, v236
	s_nop 1
	v_permlane16_swap_b32_e32 v236, v237
	v_add_f32_e32 v236, v236, v237
	v_mov_b32_e32 v237, v236
	s_nop 1
	v_permlane32_swap_b32_e32 v236, v237
	v_add_f32_e32 v236, v236, v237
	v_mul_f32_e32 v238, 0xbc800000, v236
	s_nop 0
	v_pk_add_f32 v[240:241], v[0:1], v[238:239] op_sel_hi:[1,0]
	v_pk_add_f32 v[244:245], v[2:3], v[238:239] op_sel_hi:[1,0]
	v_pk_mul_f32 v[242:243], v[240:241], v[240:241]
	v_pk_mul_f32 v[246:247], v[244:245], v[244:245]
	v_pk_add_f32 v[240:241], v[4:5], v[238:239] op_sel_hi:[1,0]
	v_pk_add_f32 v[244:245], v[6:7], v[238:239] op_sel_hi:[1,0]
	v_pk_fma_f32 v[242:243], v[240:241], v[240:241], v[242:243]
	v_pk_fma_f32 v[246:247], v[244:245], v[244:245], v[246:247]
	v_pk_add_f32 v[240:241], v[12:13], v[238:239] op_sel_hi:[1,0]
	v_pk_add_f32 v[244:245], v[14:15], v[238:239] op_sel_hi:[1,0]
	v_pk_fma_f32 v[242:243], v[240:241], v[240:241], v[242:243]
	v_pk_fma_f32 v[246:247], v[244:245], v[244:245], v[246:247]
	v_pk_add_f32 v[240:241], v[20:21], v[238:239] op_sel_hi:[1,0]
	v_pk_add_f32 v[244:245], v[22:23], v[238:239] op_sel_hi:[1,0]
	v_pk_fma_f32 v[242:243], v[240:241], v[240:241], v[242:243]
	v_pk_fma_f32 v[246:247], v[244:245], v[244:245], v[246:247]
	s_nop 0
	v_pk_add_f32 v[242:243], v[242:243], v[246:247]
	s_nop 0
	v_add_f32_e32 v237, v242, v243
	v_mov_b32_e32 v238, v237
	s_nop 1
	v_permlane16_swap_b32_e32 v237, v238
	v_add_f32_e32 v237, v237, v238
	v_mov_b32_e32 v238, v237
	s_nop 1
	v_permlane32_swap_b32_e32 v237, v238
	v_add_f32_e32 v237, v237, v238
	s_and_saveexec_b64 s[8:9], s[2:3]
	s_cbranch_execz .Lst_e4
	v_mul_f32_e32 v236, 0x3c800000, v236
	ds_write_b64 v222, v[236:237] offset:4096
.Lst_e4:
	s_or_b64 exec, exec, s[8:9]
	v_pk_add_f32 v[236:237], v[8:9], v[10:11]
	v_pk_add_f32 v[238:239], v[16:17], v[18:19]
	v_pk_add_f32 v[240:241], v[24:25], v[26:27]
	v_pk_add_f32 v[242:243], v[28:29], v[30:31]
	v_pk_add_f32 v[236:237], v[236:237], v[238:239]
	v_pk_add_f32 v[240:241], v[240:241], v[242:243]
	s_nop 0
	v_pk_add_f32 v[236:237], v[236:237], v[240:241]
	s_nop 0
	v_add_f32_e32 v236, v236, v237
	v_mov_b32_e32 v237, v236
	s_nop 1
	v_permlane16_swap_b32_e32 v236, v237
	v_add_f32_e32 v236, v236, v237
	v_mov_b32_e32 v237, v236
	s_nop 1
	v_permlane32_swap_b32_e32 v236, v237
	v_add_f32_e32 v236, v236, v237
	v_mul_f32_e32 v238, 0xbc800000, v236
	s_nop 0
	v_pk_add_f32 v[240:241], v[8:9], v[238:239] op_sel_hi:[1,0]
	v_pk_add_f32 v[244:245], v[10:11], v[238:239] op_sel_hi:[1,0]
	v_pk_mul_f32 v[242:243], v[240:241], v[240:241]
	v_pk_mul_f32 v[246:247], v[244:245], v[244:245]
	v_pk_add_f32 v[240:241], v[16:17], v[238:239] op_sel_hi:[1,0]
	v_pk_add_f32 v[244:245], v[18:19], v[238:239] op_sel_hi:[1,0]
	v_pk_fma_f32 v[242:243], v[240:241], v[240:241], v[242:243]
	v_pk_fma_f32 v[246:247], v[244:245], v[244:245], v[246:247]
	v_pk_add_f32 v[240:241], v[24:25], v[238:239] op_sel_hi:[1,0]
	v_pk_add_f32 v[244:245], v[26:27], v[238:239] op_sel_hi:[1,0]
	v_pk_fma_f32 v[242:243], v[240:241], v[240:241], v[242:243]
	v_pk_fma_f32 v[246:247], v[244:245], v[244:245], v[246:247]
	v_pk_add_f32 v[240:241], v[28:29], v[238:239] op_sel_hi:[1,0]
	v_pk_add_f32 v[244:245], v[30:31], v[238:239] op_sel_hi:[1,0]
	v_pk_fma_f32 v[242:243], v[240:241], v[240:241], v[242:243]
	v_pk_fma_f32 v[246:247], v[244:245], v[244:245], v[246:247]
	s_nop 0
	v_pk_add_f32 v[242:243], v[242:243], v[246:247]
	s_nop 0
	v_add_f32_e32 v237, v242, v243
	v_mov_b32_e32 v238, v237
	s_nop 1
	v_permlane16_swap_b32_e32 v237, v238
	v_add_f32_e32 v237, v237, v238
	v_mov_b32_e32 v238, v237
	s_nop 1
	v_permlane32_swap_b32_e32 v237, v238
	v_add_f32_e32 v237, v237, v238
	s_and_saveexec_b64 s[8:9], s[2:3]
	s_cbranch_execz .Lst_e5
	v_mul_f32_e32 v236, 0x3c800000, v236
	ds_write_b64 v222, v[236:237] offset:4608
.Lst_e5:
	s_or_b64 exec, exec, s[8:9]
	s_waitcnt vmcnt(4)
	s_nop 0
	v_cndmask_b32_e64 v189, v144, v136, s[0:1]
	v_mov_b32_e32 v190, v169
	v_cndmask_b32_e64 v188, v145, v137, s[0:1]
	v_cndmask_b32_e64 v187, v146, v138, s[0:1]
	v_mov_b32_dpp v190, v189 row_ror:8 row_mask:0xf bank_mask:0xf
	v_mov_b32_e32 v189, v169
	v_cndmask_b32_e64 v144, v190, v144, s[0:1]
	v_cndmask_b32_e64 v136, v136, v190, s[0:1]
	v_mov_b32_dpp v189, v188 row_ror:8 row_mask:0xf bank_mask:0xf
	v_cndmask_b32_e64 v145, v189, v145, s[0:1]
	v_cndmask_b32_e64 v137, v137, v189, s[0:1]
	v_mov_b32_e32 v188, v169
	v_pk_fma_f32 v[40:41], v[144:145], s[28:29], v[40:41] op_sel_hi:[1,0,1]
	v_pk_fma_f32 v[44:45], v[136:137], s[28:29], v[44:45] op_sel_hi:[1,0,1]
	v_cndmask_b32_e64 v136, v140, v132, s[0:1]
	v_mov_b32_e32 v144, v169
	v_cndmask_b32_e64 v186, v147, v139, s[0:1]
	v_mov_b32_dpp v188, v187 row_ror:8 row_mask:0xf bank_mask:0xf
	v_mov_b32_e32 v187, v169
	v_mov_b32_dpp v144, v136 row_ror:8 row_mask:0xf bank_mask:0xf
	v_cndmask_b32_e64 v137, v141, v133, s[0:1]
	v_mov_b32_dpp v187, v186 row_ror:8 row_mask:0xf bank_mask:0xf
	v_cndmask_b32_e64 v136, v144, v140, s[0:1]
	v_mov_b32_e32 v140, v169
	v_cndmask_b32_e64 v138, v138, v188, s[0:1]
	v_cndmask_b32_e64 v139, v139, v187, s[0:1]
	v_mov_b32_dpp v140, v137 row_ror:8 row_mask:0xf bank_mask:0xf
	v_pk_fma_f32 v[46:47], v[138:139], s[28:29], v[46:47] op_sel_hi:[1,0,1]
	v_cndmask_b32_e64 v138, v142, v134, s[0:1]
	v_cndmask_b32_e64 v137, v140, v141, s[0:1]
	v_cndmask_b32_e64 v133, v133, v140, s[0:1]
	v_mov_b32_e32 v140, v169
	v_cndmask_b32_e64 v139, v143, v135, s[0:1]
	v_cndmask_b32_e64 v132, v132, v144, s[0:1]
	v_mov_b32_dpp v140, v138 row_ror:8 row_mask:0xf bank_mask:0xf
	v_cndmask_b32_e64 v138, v140, v142, s[0:1]
	v_cndmask_b32_e64 v134, v134, v140, s[0:1]
	v_mov_b32_e32 v140, v169
	s_waitcnt vmcnt(0)
	v_pk_fma_f32 v[36:37], v[132:133], s[28:29], v[36:37] op_sel_hi:[1,0,1]
	v_cndmask_b32_e64 v133, v157, v149, s[0:1]
	v_mov_b32_dpp v140, v139 row_ror:8 row_mask:0xf bank_mask:0xf
	v_cndmask_b32_e64 v135, v135, v140, s[0:1]
	v_pk_fma_f32 v[38:39], v[134:135], s[28:29], v[38:39] op_sel_hi:[1,0,1]
	v_cndmask_b32_e64 v132, v156, v148, s[0:1]
	v_mov_b32_e32 v134, v169
	v_mov_b32_e32 v135, v169
	v_cndmask_b32_e64 v139, v140, v143, s[0:1]
	v_mov_b32_dpp v134, v132 row_ror:8 row_mask:0xf bank_mask:0xf
	v_mov_b32_dpp v135, v133 row_ror:8 row_mask:0xf bank_mask:0xf
	v_cndmask_b32_e64 v132, v134, v156, s[0:1]
	v_cndmask_b32_e64 v134, v148, v134, s[0:1]
	v_cndmask_b32_e64 v133, v135, v157, s[0:1]
	v_cndmask_b32_e64 v135, v149, v135, s[0:1]
	v_pk_fma_f32 v[48:49], v[132:133], s[28:29], v[48:49] op_sel_hi:[1,0,1]
	v_pk_fma_f32 v[52:53], v[134:135], s[28:29], v[52:53] op_sel_hi:[1,0,1]
	v_cndmask_b32_e64 v132, v152, v128, s[0:1]
	v_mov_b32_e32 v134, v169
	v_pk_fma_f32 v[34:35], v[138:139], s[28:29], v[34:35] op_sel_hi:[1,0,1]
	v_pk_fma_f32 v[32:33], v[136:137], s[28:29], v[32:33] op_sel_hi:[1,0,1]
	v_cndmask_b32_e64 v137, v159, v151, s[0:1]
	v_cndmask_b32_e64 v136, v158, v150, s[0:1]
	v_mov_b32_e32 v138, v169
	v_mov_b32_e32 v139, v169
	v_mov_b32_dpp v134, v132 row_ror:8 row_mask:0xf bank_mask:0xf
	v_mov_b32_dpp v138, v136 row_ror:8 row_mask:0xf bank_mask:0xf
	v_mov_b32_dpp v139, v137 row_ror:8 row_mask:0xf bank_mask:0xf
	v_cndmask_b32_e64 v133, v153, v129, s[0:1]
	v_cndmask_b32_e64 v132, v134, v152, s[0:1]
	v_cndmask_b32_e64 v134, v128, v134, s[0:1]
	v_mov_b32_e32 v128, v169
	v_mov_b32_e32 v140, v101
	v_mov_b32_e32 v141, v102
	v_mov_b32_e32 v142, v100
	v_mov_b32_e32 v143, v103
	v_cndmask_b32_e64 v136, v138, v158, s[0:1]
	v_cndmask_b32_e64 v137, v139, v159, s[0:1]
	v_mov_b32_dpp v128, v133 row_ror:8 row_mask:0xf bank_mask:0xf
	v_pk_add_f32 v[140:141], v[140:141], v[142:143]
	v_mov_b32_e32 v142, v109
	v_mov_b32_e32 v143, v110
	v_mov_b32_e32 v144, v108
	v_mov_b32_e32 v145, v111
	v_cndmask_b32_e64 v138, v150, v138, s[0:1]
	v_cndmask_b32_e64 v139, v151, v139, s[0:1]
	v_pk_fma_f32 v[50:51], v[136:137], s[28:29], v[50:51] op_sel_hi:[1,0,1]
	v_cndmask_b32_e64 v136, v154, v130, s[0:1]
	v_cndmask_b32_e64 v133, v128, v153, s[0:1]
	v_cndmask_b32_e64 v135, v129, v128, s[0:1]
	v_mov_b32_e32 v128, v169
	v_pk_add_f32 v[142:143], v[142:143], v[144:145]
	v_cndmask_b32_e64 v146, v188, v146, s[0:1]
	v_cndmask_b32_e64 v147, v187, v147, s[0:1]
	v_pk_fma_f32 v[54:55], v[138:139], s[28:29], v[54:55] op_sel_hi:[1,0,1]
	v_mov_b32_dpp v128, v136 row_ror:8 row_mask:0xf bank_mask:0xf
	v_and_b32_e32 v129, 64, v221
	v_add_f32_e32 v139, v140, v141
	v_pk_add_f32 v[142:143], v[142:143], v[142:143] op_sel_hi:[0,1]
	v_pk_fma_f32 v[42:43], v[146:147], s[28:29], v[42:43] op_sel_hi:[1,0,1]
	v_cndmask_b32_e64 v136, v128, v154, s[0:1]
	v_cndmask_b32_e64 v138, v130, v128, s[0:1]
	v_xor_b32_e32 v128, 16, v221
	v_add_u32_e32 v129, 64, v129
	v_add_f32_e32 v141, 0, v139
	v_add_f32_e32 v145, v92, v93
	v_add_f32_e32 v147, v94, v95
	v_mov_b32_e32 v144, v96
	v_mov_b32_e32 v146, v97
	v_mov_b32_e32 v142, v98
	v_mov_b32_e32 v140, v99
	v_cmp_lt_i32_e32 vcc, v128, v129
	v_pk_add_f32 v[144:145], v[144:145], v[146:147]
	v_pk_add_f32 v[140:141], v[142:143], v[140:141]
	v_cndmask_b32_e32 v128, v221, v128, vcc
	v_pk_add_f32 v[140:141], v[144:145], v[140:141]
	v_lshlrev_b32_e32 v128, 2, v128
	v_add_f32_e32 v139, v140, v141
	ds_bpermute_b32 v140, v128, v139
	v_xor_b32_e32 v141, 32, v221
	v_cmp_lt_i32_e32 vcc, v141, v129
	v_cndmask_b32_e64 v137, v155, v131, s[0:1]
	v_mov_b32_e32 v130, v169
	v_cndmask_b32_e32 v129, v221, v141, vcc
	v_lshlrev_b32_e32 v129, 2, v129
	s_waitcnt lgkmcnt(0)
	v_add_f32_e32 v140, v139, v140
	ds_bpermute_b32 v141, v129, v140
	v_mov_b32_dpp v130, v137 row_ror:8 row_mask:0xf bank_mask:0xf
	v_cndmask_b32_e64 v137, v130, v155, s[0:1]
	v_cndmask_b32_e64 v139, v131, v130, s[0:1]
	v_pk_fma_f32 v[58:59], v[136:137], s[28:29], v[58:59] op_sel_hi:[1,0,1]
	s_waitcnt lgkmcnt(0)
	v_add_f32_e32 v130, v140, v141
	v_fmamk_f32 v136, v130, 0xbc800000, v103
	v_fmamk_f32 v140, v130, 0xbc800000, v101
	v_fmamk_f32 v131, v130, 0xbc800000, v102
	v_fmamk_f32 v137, v130, 0xbc800000, v100
	v_mul_f32_e32 v140, v140, v140
	v_mul_f32_e32 v136, v136, v136
	v_fmac_f32_e32 v140, v137, v137
	v_fmac_f32_e32 v136, v131, v131
	v_fmamk_f32 v137, v130, 0xbc800000, v111
	v_fmamk_f32 v141, v130, 0xbc800000, v109
	v_add_f32_e32 v131, v140, v136
	v_fmamk_f32 v136, v130, 0xbc800000, v110
	v_fmamk_f32 v140, v130, 0xbc800000, v108
	v_mul_f32_e32 v141, v141, v141
	v_mul_f32_e32 v137, v137, v137
	v_fmac_f32_e32 v141, v140, v140
	v_fmac_f32_e32 v137, v136, v136
	v_add_f32_e32 v136, v141, v137
	v_fmamk_f32 v137, v130, 0xbc800000, v95
	v_fmamk_f32 v141, v130, 0xbc800000, v93
	v_add_f32_e32 v131, v131, v136
	v_fmamk_f32 v136, v130, 0xbc800000, v94
	v_fmamk_f32 v140, v130, 0xbc800000, v92
	v_mul_f32_e32 v141, v141, v141
	v_mul_f32_e32 v137, v137, v137
	v_fmac_f32_e32 v141, v140, v140
	v_fmac_f32_e32 v137, v136, v136
	v_add_f32_e32 v136, v141, v137
	v_mov_b32_e32 v141, v97
	v_fmamk_f32 v137, v130, 0xbc800000, v99
	v_fmac_f32_e32 v141, 0xbc800000, v130
	v_add_f32_e32 v131, v136, v131
	v_fmamk_f32 v136, v130, 0xbc800000, v98
	v_fmamk_f32 v140, v130, 0xbc800000, v96
	v_mul_f32_e32 v141, v141, v141
	v_mul_f32_e32 v137, v137, v137
	v_fmac_f32_e32 v141, v140, v140
	v_fmac_f32_e32 v137, v136, v136
	v_add_f32_e32 v136, v141, v137
	v_add_f32_e32 v131, v136, v131
	ds_bpermute_b32 v136, v128, v131
	v_pk_fma_f32 v[56:57], v[132:133], s[28:29], v[56:57] op_sel_hi:[1,0,1]
	v_pk_fma_f32 v[62:63], v[138:139], s[28:29], v[62:63] op_sel_hi:[1,0,1]
	v_pk_fma_f32 v[60:61], v[134:135], s[28:29], v[60:61] op_sel_hi:[1,0,1]
	s_waitcnt lgkmcnt(0)
	v_add_f32_e32 v131, v131, v136
	ds_bpermute_b32 v132, v129, v131
	s_and_saveexec_b64 s[8:9], s[2:3]
	s_cbranch_execz .LBB0_502
	v_mul_f32_e32 v130, 0x3c800000, v130
	s_waitcnt lgkmcnt(0)
	v_add_f32_e32 v131, v131, v132
	ds_write_b64 v222, v[130:131]
.LBB0_502:
	s_or_b64 exec, exec, s[8:9]
.LBB0_504:
	s_or_b64 exec, exec, s[8:9]
.LBB0_506:
	s_or_b64 exec, exec, s[8:9]
.LBB0_508:
	s_or_b64 exec, exec, s[8:9]
.LBB0_510:
	s_or_b64 exec, exec, s[8:9]
.LBB0_512:
	s_or_b64 exec, exec, s[8:9]
	s_waitcnt lgkmcnt(0)
	v_pk_add_f32 v[130:131], v[32:33], v[34:35]
	v_pk_add_f32 v[132:133], v[36:37], v[38:39]
	v_pk_add_f32 v[134:135], v[40:41], v[42:43]
	v_pk_add_f32 v[136:137], v[44:45], v[46:47]
	v_pk_add_f32 v[130:131], v[130:131], v[132:133]
	v_pk_add_f32 v[134:135], v[134:135], v[136:137]
	s_nop 0
	v_pk_add_f32 v[130:131], v[130:131], v[134:135]
	s_nop 0
	v_add_f32_e32 v130, v130, v131
	v_mov_b32_e32 v131, v130
	s_nop 1
	v_permlane16_swap_b32_e32 v130, v131
	v_add_f32_e32 v130, v130, v131
	v_mov_b32_e32 v131, v130
	s_nop 1
	v_permlane32_swap_b32_e32 v130, v131
	v_add_f32_e32 v130, v130, v131
	v_mul_f32_e32 v132, 0xbc800000, v130
	s_nop 0
	v_pk_add_f32 v[134:135], v[32:33], v[132:133] op_sel_hi:[1,0]
	v_pk_add_f32 v[138:139], v[34:35], v[132:133] op_sel_hi:[1,0]
	v_pk_mul_f32 v[136:137], v[134:135], v[134:135]
	v_pk_mul_f32 v[140:141], v[138:139], v[138:139]
	v_pk_add_f32 v[134:135], v[36:37], v[132:133] op_sel_hi:[1,0]
	v_pk_add_f32 v[138:139], v[38:39], v[132:133] op_sel_hi:[1,0]
	v_pk_fma_f32 v[136:137], v[134:135], v[134:135], v[136:137]
	v_pk_fma_f32 v[140:141], v[138:139], v[138:139], v[140:141]
	v_pk_add_f32 v[134:135], v[40:41], v[132:133] op_sel_hi:[1,0]
	v_pk_add_f32 v[138:139], v[42:43], v[132:133] op_sel_hi:[1,0]
	v_pk_fma_f32 v[136:137], v[134:135], v[134:135], v[136:137]
	v_pk_fma_f32 v[140:141], v[138:139], v[138:139], v[140:141]
	v_pk_add_f32 v[134:135], v[44:45], v[132:133] op_sel_hi:[1,0]
	v_pk_add_f32 v[138:139], v[46:47], v[132:133] op_sel_hi:[1,0]
	v_pk_fma_f32 v[136:137], v[134:135], v[134:135], v[136:137]
	v_pk_fma_f32 v[140:141], v[138:139], v[138:139], v[140:141]
	s_nop 0
	v_pk_add_f32 v[136:137], v[136:137], v[140:141]
	s_nop 0
	v_add_f32_e32 v131, v136, v137
	v_mov_b32_e32 v132, v131
	s_nop 1
	v_permlane16_swap_b32_e32 v131, v132
	v_add_f32_e32 v131, v131, v132
	v_mov_b32_e32 v132, v131
	s_nop 1
	v_permlane32_swap_b32_e32 v131, v132
	v_add_f32_e32 v131, v131, v132
	s_and_saveexec_b64 s[8:9], s[2:3]
	s_cbranch_execz .LBB0_514
	v_mul_f32_e32 v130, 0x3c800000, v130
	ds_write_b64 v222, v[130:131] offset:5120
